# top-k cut bit-loop: popcounts split between SALU (s_bcnt1) and VALU (v_bcnt_u32_b32) so two co-resident waves overlap scalar and vector issue
# speedup vs baseline: 1.0216x; 1.0014x over previous
; template <int LIM> DI int topk_cut(LAS unsigned* cand, int cnt, unsigned& tauq, int lane) {
;     ...
;     const unsigned cv = V | (1u << bit); int c = 0;
; #pragma unroll
;     for (int i = 0; i < NE; ++i) c += __popcll(__ballot(e[i] >= cv));
;     if (c >= 256) V = cv;
;     if (c >= 256 && c <= LIM) break;
;   }
.Lmy_cut_loop:
	s_lshl_b32 s100, 1, s99
	s_or_b32 s100, s98, s100
	v_cmp_ge_u32_e64 s[18:19], v2, s100
	v_cmp_ge_u32_e64 s[20:21], v3, s100
	v_cmp_le_u32_e32 vcc, s100, v4
	v_bcnt_u32_b32 v16, s18, 0
	v_bcnt_u32_b32 v16, s19, v16
	v_bcnt_u32_b32 v16, s20, v16
	v_bcnt_u32_b32 v16, s21, v16
	s_bcnt1_i32_b64 s2, vcc
	v_cmp_ge_u32_e64 s[18:19], v5, s100
	v_cmp_ge_u32_e64 s[20:21], v6, s100
	v_cmp_le_u32_e32 vcc, s100, v7
	v_bcnt_u32_b32 v16, s18, v16
	v_bcnt_u32_b32 v16, s19, v16
	s_bcnt1_i32_b64 s20, s[20:21]
	s_bcnt1_i32_b64 s101, vcc
	s_add_i32 s2, s2, s20
	s_add_i32 s2, s2, s101
	v_cmp_ge_u32_e64 s[18:19], v8, s100
	v_cmp_ge_u32_e64 s[20:21], v9, s100
	v_cmp_le_u32_e32 vcc, s100, v10
	v_bcnt_u32_b32 v16, s18, v16
	v_bcnt_u32_b32 v16, s19, v16
	v_bcnt_u32_b32 v16, s20, v16
	v_bcnt_u32_b32 v16, s21, v16
	s_bcnt1_i32_b64 s101, vcc
	s_add_i32 s2, s2, s101
	v_cmp_ge_u32_e64 s[18:19], v11, s100
	v_cmp_ge_u32_e64 s[20:21], v12, s100
	v_cmp_le_u32_e32 vcc, s100, v13
	v_bcnt_u32_b32 v16, s18, v16
	v_bcnt_u32_b32 v16, s19, v16
	s_bcnt1_i32_b64 s20, s[20:21]
	s_bcnt1_i32_b64 s101, vcc
	s_add_i32 s2, s2, s20
	s_add_i32 s2, s2, s101
	v_readfirstlane_b32 s18, v16
	s_add_i32 s2, s2, s18
	s_cmp_ge_u32 s2, 0x100
	s_cselect_b32 s98, s100, s98
	s_cbranch_scc0 .Lmy_cut_next
	s_cmp_le_u32 s2, s31
	s_cbranch_scc1 .Lmy_cut_done
